# norm phase: do not wait on the row's own stores at the loop latch when the bf16 h row is also stored (counted vmcnt per path)
# speedup vs baseline: 1.0025x; 1.0025x over previous
; DI float bflo(unsigned v) { return __uint_as_float(v << 16); }
; DI float bfhi(unsigned v) { return __uint_as_float(v & 0xffff0000u); }
; DI unsigned pk2(float lo, float hi) { f32x2 v = {lo, hi}; bf2_t r = __builtin_convertvector(v, bf2_t); return __builtin_bit_cast(unsigned, r); }
; DI float wave_sum(float v) { return row_sum16(xadd16(xadd32(v))); }
; DI void phase_norm(const Params& p, int l, int mode) {
;     ...
;     while (row < MTOK) {
;         const int nrow = row + stride;
;         f32x4 n0 = a0, n1 = a1, n2 = a2, n3 = a3; u32x4 m0 = o0, m1 = o1;
;         if (nrow < MTOK) load_row(nrow, n0, n1, n2, n3, m0, m1);
;         float v[16];
; #pragma unroll
;         for (int i = 0; i < 4; ++i) { v[i] = a0[i]; v[4 + i] = a1[i]; v[8 + i] = a2[i]; v[12 + i] = a3[i]; }
;         if (mode == 1) {
;             float ov[16];
; #pragma unroll
;             for (int i = 0; i < 4; ++i) { ov[2 * i] = bflo(o0[i]); ov[2 * i + 1] = bfhi(o0[i]); ov[8 + 2 * i] = bflo(o1[i]); ov[8 + 2 * i + 1] = bfhi(o1[i]); }
;             float ss = 0.f;
; #pragma unroll
;             for (int i = 0; i < 16; ++i) ss += ov[i] * ov[i];
;             ss = wave_sum(ss);
;             const float rstd = rsqrtf(ss * (1.f / 1024.f) + EPS);
; #pragma unroll
;             for (int i = 0; i < 16; ++i) v[i] += ov[i] * rstd * gp[i];
;             float* dst = res_dst(p, row);
;             *(f32x4*)(dst + c0) = (f32x4){v[0], v[1], v[2], v[3]}; *(f32x4*)(dst + c0 + 4) = (f32x4){v[4], v[5], v[6], v[7]};
;             *(f32x4*)(dst + 512 + c0) = (f32x4){v[8], v[9], v[10], v[11]}; *(f32x4*)(dst + 512 + c0 + 4) = (f32x4){v[12], v[13], v[14], v[15]};
;         }
;         if (do_h) {
;             float ss = 0.f;
; #pragma unroll
;             for (int i = 0; i < 16; ++i) ss += v[i] * v[i];
;             ss = wave_sum(ss);
;             const float rstd = rsqrtf(ss * (1.f / 1024.f) + EPS);
;             float hv[16];
; #pragma unroll
;             for (int i = 0; i < 16; ++i) hv[i] = v[i] * rstd * gq[i];
;             bf16_t* hrow = h + (size_t)row * 1024;
;             *(u32x4*)(hrow + c0) = (u32x4){pk2(hv[0], hv[1]), pk2(hv[2], hv[3]), pk2(hv[4], hv[5]), pk2(hv[6], hv[7])};
;             *(u32x4*)(hrow + 512 + c0) = (u32x4){pk2(hv[8], hv[9]), pk2(hv[10], hv[11]), pk2(hv[12], hv[13]), pk2(hv[14], hv[15])};
;         }
;         a0 = n0; a1 = n1; a2 = n2; a3 = n3; o0 = m0; o1 = m1; row = nrow;
.LBB0_307:
	s_waitcnt vmcnt(8)
	v_mov_b64_e32 v[64:65], v[52:53]
	v_mov_b64_e32 v[34:35], v[46:47]
	s_waitcnt vmcnt(6)
	v_mov_b64_e32 v[42:43], v[58:59]
	v_mov_b64_e32 v[38:39], v[54:55]
	s_and_b64 vcc, exec, s[44:45]
	s_cbranch_vccnz .Lnm_a
	s_waitcnt vmcnt(5)
.Lnm_a:
	v_mov_b64_e32 v[76:77], v[72:73]
	s_cbranch_vccnz .Lnm_b
	s_waitcnt vmcnt(4)
.Lnm_b:
	v_mov_b64_e32 v[80:81], v[68:69]
	v_lshl_add_u64 v[84:85], v[84:85], 0, s[28:29]
	v_lshl_add_u64 v[86:87], v[86:87], 0, s[28:29]
	v_mov_b32_e32 v99, v1
	v_mov_b64_e32 v[62:63], v[50:51]
	v_mov_b64_e32 v[36:37], v[48:49]
	v_mov_b64_e32 v[44:45], v[60:61]
	v_mov_b64_e32 v[40:41], v[56:57]
	v_mov_b64_e32 v[74:75], v[70:71]
	v_mov_b64_e32 v[78:79], v[66:67]
	s_andn2_b64 exec, exec, s[46:47]
	s_cbranch_execz .LBB0_324
